# v10 plus static priority on the other half: flips deleted in the 10 GEMM K loops, waves 0-3 raised to priority 1 once before each loop
# baseline (speedup 1.0000x reference)
.LBB0_232:
	s_ashr_i32 s25, s24, 31
	s_lshl_b64 s[26:27], s[24:25], 21
	s_add_u32 s26, s46, s26
	s_addc_u32 s27, s47, s27
	s_and_b64 s[28:29], s[2:3], exec
	s_cselect_b32 s25, s27, s35
	s_cselect_b32 s64, s26, s34
	s_ashr_i32 s23, s22, 31
	s_lshl_b64 s[28:29], s[22:23], 21
	s_add_u32 s28, s48, s28
	s_addc_u32 s29, s49, s29
	s_and_b64 s[38:39], s[2:3], exec
	s_cselect_b32 s23, s29, s37
	s_cselect_b32 s65, s28, s36
	s_add_u32 s66, s36, 0x100
	s_addc_u32 s67, s37, 0
	s_add_u32 s34, s34, 0x100080
	v_mov_b32_e32 v0, 0
	s_addc_u32 s35, s35, 0
	s_mov_b32 s68, -2
	v_mov_b32_e32 v1, v0
	v_mov_b32_e32 v2, v0
	v_mov_b32_e32 v3, v0
	v_mov_b32_e32 v4, v0
	v_mov_b32_e32 v5, v0
	v_mov_b32_e32 v6, v0
	v_mov_b32_e32 v7, v0
	v_mov_b32_e32 v12, v0
	v_mov_b32_e32 v13, v0
	v_mov_b32_e32 v14, v0
	v_mov_b32_e32 v15, v0
	v_mov_b32_e32 v20, v0
	v_mov_b32_e32 v21, v0
	v_mov_b32_e32 v22, v0
	v_mov_b32_e32 v23, v0
	v_mov_b32_e32 v28, v0
	v_mov_b32_e32 v29, v0
	v_mov_b32_e32 v30, v0
	v_mov_b32_e32 v31, v0
	v_mov_b32_e32 v36, v0
	v_mov_b32_e32 v37, v0
	v_mov_b32_e32 v38, v0
	v_mov_b32_e32 v39, v0
	v_mov_b32_e32 v44, v0
	v_mov_b32_e32 v45, v0
	v_mov_b32_e32 v46, v0
	v_mov_b32_e32 v47, v0
	v_mov_b32_e32 v52, v0
	v_mov_b32_e32 v53, v0
	v_mov_b32_e32 v54, v0
	v_mov_b32_e32 v55, v0
	v_mov_b32_e32 v8, v0
	v_mov_b32_e32 v9, v0
	v_mov_b32_e32 v10, v0
	v_mov_b32_e32 v11, v0
	v_mov_b32_e32 v16, v0
	v_mov_b32_e32 v17, v0
	v_mov_b32_e32 v18, v0
	v_mov_b32_e32 v19, v0
	v_mov_b32_e32 v24, v0
	v_mov_b32_e32 v25, v0
	v_mov_b32_e32 v26, v0
	v_mov_b32_e32 v27, v0
	v_mov_b32_e32 v32, v0
	v_mov_b32_e32 v33, v0
	v_mov_b32_e32 v34, v0
	v_mov_b32_e32 v35, v0
	v_mov_b32_e32 v40, v0
	v_mov_b32_e32 v41, v0
	v_mov_b32_e32 v42, v0
	v_mov_b32_e32 v43, v0
	v_mov_b32_e32 v48, v0
	v_mov_b32_e32 v49, v0
	v_mov_b32_e32 v50, v0
	v_mov_b32_e32 v51, v0
	v_mov_b32_e32 v56, v0
	v_mov_b32_e32 v57, v0
	v_mov_b32_e32 v58, v0
	v_mov_b32_e32 v59, v0
	v_mov_b32_e32 v60, v0
	v_mov_b32_e32 v61, v0
	v_mov_b32_e32 v62, v0
	v_mov_b32_e32 v63, v0
	v_mov_b32_e32 v64, v0
	v_mov_b32_e32 v65, v0
	v_mov_b32_e32 v66, v0
	v_mov_b32_e32 v67, v0
	v_mov_b32_e32 v68, v0
	v_mov_b32_e32 v69, v0
	v_mov_b32_e32 v70, v0
	v_mov_b32_e32 v71, v0
	v_mov_b32_e32 v80, v0
	v_mov_b32_e32 v81, v0
	v_mov_b32_e32 v82, v0
	v_mov_b32_e32 v83, v0
	v_mov_b32_e32 v84, v0
	v_mov_b32_e32 v85, v0
	v_mov_b32_e32 v86, v0
	v_mov_b32_e32 v87, v0
	v_mov_b32_e32 v96, v0
	v_mov_b32_e32 v97, v0
	v_mov_b32_e32 v98, v0
	v_mov_b32_e32 v99, v0
	v_mov_b32_e32 v100, v0
	v_mov_b32_e32 v101, v0
	v_mov_b32_e32 v102, v0
	v_mov_b32_e32 v103, v0
	v_mov_b32_e32 v112, v0
	v_mov_b32_e32 v113, v0
	v_mov_b32_e32 v114, v0
	v_mov_b32_e32 v115, v0
	v_mov_b32_e32 v116, v0
	v_mov_b32_e32 v117, v0
	v_mov_b32_e32 v118, v0
	v_mov_b32_e32 v119, v0
	v_mov_b32_e32 v72, v0
	v_mov_b32_e32 v73, v0
	v_mov_b32_e32 v74, v0
	v_mov_b32_e32 v75, v0
	v_mov_b32_e32 v76, v0
	v_mov_b32_e32 v77, v0
	v_mov_b32_e32 v78, v0
	v_mov_b32_e32 v79, v0
	v_mov_b32_e32 v88, v0
	v_mov_b32_e32 v89, v0
	v_mov_b32_e32 v90, v0
	v_mov_b32_e32 v91, v0
	v_mov_b32_e32 v92, v0
	v_mov_b32_e32 v93, v0
	v_mov_b32_e32 v94, v0
	v_mov_b32_e32 v95, v0
	v_mov_b32_e32 v104, v0
	v_mov_b32_e32 v105, v0
	v_mov_b32_e32 v106, v0
	v_mov_b32_e32 v107, v0
	v_mov_b32_e32 v108, v0
	v_mov_b32_e32 v109, v0
	v_mov_b32_e32 v110, v0
	v_mov_b32_e32 v111, v0
	v_mov_b32_e32 v120, v0
	v_mov_b32_e32 v121, v0
	v_mov_b32_e32 v122, v0
	v_mov_b32_e32 v123, v0
	v_mov_b32_e32 v124, v0
	v_mov_b32_e32 v125, v0
	v_mov_b32_e32 v126, v0
	v_mov_b32_e32 v127, v0
	s_cmp_lt_u32 s81, 4
	s_cbranch_scc0 .Lsp_skip0
	s_setprio 1

.LBB0_253:
	s_add_u32 s65, s26, 0x100
	v_mov_b32_e32 v0, 0
	s_addc_u32 s66, s27, 0
	s_mov_b32 s67, -2
	v_mov_b32_e32 v1, v0
	v_mov_b32_e32 v2, v0
	v_mov_b32_e32 v3, v0
	v_mov_b32_e32 v4, v0
	v_mov_b32_e32 v5, v0
	v_mov_b32_e32 v6, v0
	v_mov_b32_e32 v7, v0
	v_mov_b32_e32 v8, v0
	v_mov_b32_e32 v9, v0
	v_mov_b32_e32 v10, v0
	v_mov_b32_e32 v11, v0
	v_mov_b32_e32 v16, v0
	v_mov_b32_e32 v17, v0
	v_mov_b32_e32 v18, v0
	v_mov_b32_e32 v19, v0
	v_mov_b32_e32 v24, v0
	v_mov_b32_e32 v25, v0
	v_mov_b32_e32 v26, v0
	v_mov_b32_e32 v27, v0
	v_mov_b32_e32 v32, v0
	v_mov_b32_e32 v33, v0
	v_mov_b32_e32 v34, v0
	v_mov_b32_e32 v35, v0
	v_mov_b32_e32 v40, v0
	v_mov_b32_e32 v41, v0
	v_mov_b32_e32 v42, v0
	v_mov_b32_e32 v43, v0
	v_mov_b32_e32 v48, v0
	v_mov_b32_e32 v49, v0
	v_mov_b32_e32 v50, v0
	v_mov_b32_e32 v51, v0
	v_mov_b32_e32 v12, v0
	v_mov_b32_e32 v13, v0
	v_mov_b32_e32 v14, v0
	v_mov_b32_e32 v15, v0
	v_mov_b32_e32 v20, v0
	v_mov_b32_e32 v21, v0
	v_mov_b32_e32 v22, v0
	v_mov_b32_e32 v23, v0
	v_mov_b32_e32 v28, v0
	v_mov_b32_e32 v29, v0
	v_mov_b32_e32 v30, v0
	v_mov_b32_e32 v31, v0
	v_mov_b32_e32 v36, v0
	v_mov_b32_e32 v37, v0
	v_mov_b32_e32 v38, v0
	v_mov_b32_e32 v39, v0
	v_mov_b32_e32 v44, v0
	v_mov_b32_e32 v45, v0
	v_mov_b32_e32 v46, v0
	v_mov_b32_e32 v47, v0
	v_mov_b32_e32 v52, v0
	v_mov_b32_e32 v53, v0
	v_mov_b32_e32 v54, v0
	v_mov_b32_e32 v55, v0
	v_mov_b32_e32 v56, v0
	v_mov_b32_e32 v57, v0
	v_mov_b32_e32 v58, v0
	v_mov_b32_e32 v59, v0
	v_mov_b32_e32 v60, v0
	v_mov_b32_e32 v61, v0
	v_mov_b32_e32 v62, v0
	v_mov_b32_e32 v63, v0
	v_mov_b32_e32 v64, v0
	v_mov_b32_e32 v65, v0
	v_mov_b32_e32 v66, v0
	v_mov_b32_e32 v67, v0
	v_mov_b32_e32 v68, v0
	v_mov_b32_e32 v69, v0
	v_mov_b32_e32 v70, v0
	v_mov_b32_e32 v71, v0
	v_mov_b32_e32 v72, v0
	v_mov_b32_e32 v73, v0
	v_mov_b32_e32 v74, v0
	v_mov_b32_e32 v75, v0
	v_mov_b32_e32 v80, v0
	v_mov_b32_e32 v81, v0
	v_mov_b32_e32 v82, v0
	v_mov_b32_e32 v83, v0
	v_mov_b32_e32 v88, v0
	v_mov_b32_e32 v89, v0
	v_mov_b32_e32 v90, v0
	v_mov_b32_e32 v91, v0
	v_mov_b32_e32 v96, v0
	v_mov_b32_e32 v97, v0
	v_mov_b32_e32 v98, v0
	v_mov_b32_e32 v99, v0
	v_mov_b32_e32 v104, v0
	v_mov_b32_e32 v105, v0
	v_mov_b32_e32 v106, v0
	v_mov_b32_e32 v107, v0
	v_mov_b32_e32 v112, v0
	v_mov_b32_e32 v113, v0
	v_mov_b32_e32 v114, v0
	v_mov_b32_e32 v115, v0
	v_mov_b32_e32 v76, v0
	v_mov_b32_e32 v77, v0
	v_mov_b32_e32 v78, v0
	v_mov_b32_e32 v79, v0
	v_mov_b32_e32 v84, v0
	v_mov_b32_e32 v85, v0
	v_mov_b32_e32 v86, v0
	v_mov_b32_e32 v87, v0
	v_mov_b32_e32 v92, v0
	v_mov_b32_e32 v93, v0
	v_mov_b32_e32 v94, v0
	v_mov_b32_e32 v95, v0
	v_mov_b32_e32 v100, v0
	v_mov_b32_e32 v101, v0
	v_mov_b32_e32 v102, v0
	v_mov_b32_e32 v103, v0
	v_mov_b32_e32 v108, v0
	v_mov_b32_e32 v109, v0
	v_mov_b32_e32 v110, v0
	v_mov_b32_e32 v111, v0
	v_mov_b32_e32 v116, v0
	v_mov_b32_e32 v117, v0
	v_mov_b32_e32 v118, v0
	v_mov_b32_e32 v119, v0
	v_mov_b32_e32 v120, v0
	v_mov_b32_e32 v121, v0
	v_mov_b32_e32 v122, v0
	v_mov_b32_e32 v123, v0
	v_mov_b32_e32 v124, v0
	v_mov_b32_e32 v125, v0
	v_mov_b32_e32 v126, v0
	v_mov_b32_e32 v127, v0
	s_cmp_lt_u32 s81, 4
	s_cbranch_scc0 .Lsp_skip1
	s_setprio 1

.LBB0_280:
	s_ashr_i32 s23, s22, 31
	s_lshl_b64 s[24:25], s[22:23], 20
	s_add_u32 s24, s39, s24
	s_addc_u32 s25, s45, s25
	s_and_b64 s[26:27], s[2:3], exec
	s_cselect_b32 s23, s25, s35
	s_cselect_b32 s57, s24, s34
	s_ashr_i32 s21, s20, 31
	s_lshl_b64 s[26:27], s[20:21], 20
	s_add_u32 s26, s46, s26
	s_addc_u32 s27, s47, s27
	s_and_b64 s[36:37], s[2:3], exec
	s_cselect_b32 s21, s27, s31
	s_cselect_b32 s58, s26, s30
	s_add_u32 s59, s30, 0x100
	s_addc_u32 s60, s31, 0
	s_add_u32 s30, s34, 0x80080
	v_mov_b32_e32 v0, 0
	s_addc_u32 s31, s35, 0
	s_mov_b32 s61, -2
	v_mov_b32_e32 v1, v0
	v_mov_b32_e32 v2, v0
	v_mov_b32_e32 v3, v0
	v_mov_b32_e32 v4, v0
	v_mov_b32_e32 v5, v0
	v_mov_b32_e32 v6, v0
	v_mov_b32_e32 v7, v0
	v_mov_b32_e32 v16, v0
	v_mov_b32_e32 v17, v0
	v_mov_b32_e32 v18, v0
	v_mov_b32_e32 v19, v0
	v_mov_b32_e32 v20, v0
	v_mov_b32_e32 v21, v0
	v_mov_b32_e32 v22, v0
	v_mov_b32_e32 v23, v0
	v_mov_b32_e32 v32, v0
	v_mov_b32_e32 v33, v0
	v_mov_b32_e32 v34, v0
	v_mov_b32_e32 v35, v0
	v_mov_b32_e32 v36, v0
	v_mov_b32_e32 v37, v0
	v_mov_b32_e32 v38, v0
	v_mov_b32_e32 v39, v0
	v_mov_b32_e32 v48, v0
	v_mov_b32_e32 v49, v0
	v_mov_b32_e32 v50, v0
	v_mov_b32_e32 v51, v0
	v_mov_b32_e32 v52, v0
	v_mov_b32_e32 v53, v0
	v_mov_b32_e32 v54, v0
	v_mov_b32_e32 v55, v0
	v_mov_b32_e32 v8, v0
	v_mov_b32_e32 v9, v0
	v_mov_b32_e32 v10, v0
	v_mov_b32_e32 v11, v0
	v_mov_b32_e32 v12, v0
	v_mov_b32_e32 v13, v0
	v_mov_b32_e32 v14, v0
	v_mov_b32_e32 v15, v0
	v_mov_b32_e32 v24, v0
	v_mov_b32_e32 v25, v0
	v_mov_b32_e32 v26, v0
	v_mov_b32_e32 v27, v0
	v_mov_b32_e32 v28, v0
	v_mov_b32_e32 v29, v0
	v_mov_b32_e32 v30, v0
	v_mov_b32_e32 v31, v0
	v_mov_b32_e32 v40, v0
	v_mov_b32_e32 v41, v0
	v_mov_b32_e32 v42, v0
	v_mov_b32_e32 v43, v0
	v_mov_b32_e32 v44, v0
	v_mov_b32_e32 v45, v0
	v_mov_b32_e32 v46, v0
	v_mov_b32_e32 v47, v0
	v_mov_b32_e32 v56, v0
	v_mov_b32_e32 v57, v0
	v_mov_b32_e32 v58, v0
	v_mov_b32_e32 v59, v0
	v_mov_b32_e32 v60, v0
	v_mov_b32_e32 v61, v0
	v_mov_b32_e32 v62, v0
	v_mov_b32_e32 v63, v0
	v_mov_b32_e32 v64, v0
	v_mov_b32_e32 v65, v0
	v_mov_b32_e32 v66, v0
	v_mov_b32_e32 v67, v0
	v_mov_b32_e32 v68, v0
	v_mov_b32_e32 v69, v0
	v_mov_b32_e32 v70, v0
	v_mov_b32_e32 v71, v0
	v_mov_b32_e32 v80, v0
	v_mov_b32_e32 v81, v0
	v_mov_b32_e32 v82, v0
	v_mov_b32_e32 v83, v0
	v_mov_b32_e32 v84, v0
	v_mov_b32_e32 v85, v0
	v_mov_b32_e32 v86, v0
	v_mov_b32_e32 v87, v0
	v_mov_b32_e32 v96, v0
	v_mov_b32_e32 v97, v0
	v_mov_b32_e32 v98, v0
	v_mov_b32_e32 v99, v0
	v_mov_b32_e32 v100, v0
	v_mov_b32_e32 v101, v0
	v_mov_b32_e32 v102, v0
	v_mov_b32_e32 v103, v0
	v_mov_b32_e32 v112, v0
	v_mov_b32_e32 v113, v0
	v_mov_b32_e32 v114, v0
	v_mov_b32_e32 v115, v0
	v_mov_b32_e32 v116, v0
	v_mov_b32_e32 v117, v0
	v_mov_b32_e32 v118, v0
	v_mov_b32_e32 v119, v0
	v_mov_b32_e32 v72, v0
	v_mov_b32_e32 v73, v0
	v_mov_b32_e32 v74, v0
	v_mov_b32_e32 v75, v0
	v_mov_b32_e32 v76, v0
	v_mov_b32_e32 v77, v0
	v_mov_b32_e32 v78, v0
	v_mov_b32_e32 v79, v0
	v_mov_b32_e32 v88, v0
	v_mov_b32_e32 v89, v0
	v_mov_b32_e32 v90, v0
	v_mov_b32_e32 v91, v0
	v_mov_b32_e32 v92, v0
	v_mov_b32_e32 v93, v0
	v_mov_b32_e32 v94, v0
	v_mov_b32_e32 v95, v0
	v_mov_b32_e32 v104, v0
	v_mov_b32_e32 v105, v0
	v_mov_b32_e32 v106, v0
	v_mov_b32_e32 v107, v0
	v_mov_b32_e32 v108, v0
	v_mov_b32_e32 v109, v0
	v_mov_b32_e32 v110, v0
	v_mov_b32_e32 v111, v0
	v_mov_b32_e32 v120, v0
	v_mov_b32_e32 v121, v0
	v_mov_b32_e32 v122, v0
	v_mov_b32_e32 v123, v0
	v_mov_b32_e32 v124, v0
	v_mov_b32_e32 v125, v0
	v_mov_b32_e32 v126, v0
	v_mov_b32_e32 v127, v0
	s_cmp_lt_u32 s81, 4
	s_cbranch_scc0 .Lsp_skip2
	s_setprio 1

.LBB0_450:
	s_ashr_i32 s21, s20, 31
	s_lshl_b64 s[22:23], s[20:21], 21
	s_add_u32 s22, s33, s22
	s_addc_u32 s23, s38, s23
	s_and_b64 s[24:25], s[4:5], exec
	s_cselect_b32 s21, s23, s35
	s_cselect_b32 s27, s22, s34
	s_ashr_i32 s19, s18, 31
	s_lshl_b64 s[24:25], s[18:19], 21
	s_add_u32 s24, s39, s24
	s_addc_u32 s25, s40, s25
	s_and_b64 s[36:37], s[4:5], exec
	s_cselect_b32 s19, s25, s31
	s_cselect_b32 s55, s24, s30
	s_add_u32 s56, s30, 0x100
	s_addc_u32 s57, s31, 0
	s_add_u32 s30, s34, 0x100080
	v_mov_b32_e32 v0, 0
	s_addc_u32 s31, s35, 0
	s_mov_b32 s58, -2
	s_waitcnt lgkmcnt(0)
	v_mov_b32_e32 v1, v0
	v_mov_b32_e32 v2, v0
	v_mov_b32_e32 v3, v0
	v_mov_b32_e32 v4, v0
	v_mov_b32_e32 v5, v0
	v_mov_b32_e32 v6, v0
	v_mov_b32_e32 v7, v0
	v_mov_b32_e32 v16, v0
	v_mov_b32_e32 v17, v0
	v_mov_b32_e32 v18, v0
	v_mov_b32_e32 v19, v0
	v_mov_b32_e32 v20, v0
	v_mov_b32_e32 v21, v0
	v_mov_b32_e32 v22, v0
	v_mov_b32_e32 v23, v0
	v_mov_b32_e32 v32, v0
	v_mov_b32_e32 v33, v0
	v_mov_b32_e32 v34, v0
	v_mov_b32_e32 v35, v0
	v_mov_b32_e32 v36, v0
	v_mov_b32_e32 v37, v0
	v_mov_b32_e32 v38, v0
	v_mov_b32_e32 v39, v0
	v_mov_b32_e32 v48, v0
	v_mov_b32_e32 v49, v0
	v_mov_b32_e32 v50, v0
	v_mov_b32_e32 v51, v0
	v_mov_b32_e32 v52, v0
	v_mov_b32_e32 v53, v0
	v_mov_b32_e32 v54, v0
	v_mov_b32_e32 v55, v0
	v_mov_b32_e32 v8, v0
	v_mov_b32_e32 v9, v0
	v_mov_b32_e32 v10, v0
	v_mov_b32_e32 v11, v0
	v_mov_b32_e32 v12, v0
	v_mov_b32_e32 v13, v0
	v_mov_b32_e32 v14, v0
	v_mov_b32_e32 v15, v0
	v_mov_b32_e32 v24, v0
	v_mov_b32_e32 v25, v0
	v_mov_b32_e32 v26, v0
	v_mov_b32_e32 v27, v0
	v_mov_b32_e32 v28, v0
	v_mov_b32_e32 v29, v0
	v_mov_b32_e32 v30, v0
	v_mov_b32_e32 v31, v0
	v_mov_b32_e32 v40, v0
	v_mov_b32_e32 v41, v0
	v_mov_b32_e32 v42, v0
	v_mov_b32_e32 v43, v0
	v_mov_b32_e32 v44, v0
	v_mov_b32_e32 v45, v0
	v_mov_b32_e32 v46, v0
	v_mov_b32_e32 v47, v0
	v_mov_b32_e32 v56, v0
	v_mov_b32_e32 v57, v0
	v_mov_b32_e32 v58, v0
	v_mov_b32_e32 v59, v0
	v_mov_b32_e32 v60, v0
	v_mov_b32_e32 v61, v0
	v_mov_b32_e32 v62, v0
	v_mov_b32_e32 v63, v0
	v_mov_b32_e32 v64, v0
	v_mov_b32_e32 v65, v0
	v_mov_b32_e32 v66, v0
	v_mov_b32_e32 v67, v0
	v_mov_b32_e32 v68, v0
	v_mov_b32_e32 v69, v0
	v_mov_b32_e32 v70, v0
	v_mov_b32_e32 v71, v0
	v_mov_b32_e32 v80, v0
	v_mov_b32_e32 v81, v0
	v_mov_b32_e32 v82, v0
	v_mov_b32_e32 v83, v0
	v_mov_b32_e32 v84, v0
	v_mov_b32_e32 v85, v0
	v_mov_b32_e32 v86, v0
	v_mov_b32_e32 v87, v0
	v_mov_b32_e32 v96, v0
	v_mov_b32_e32 v97, v0
	v_mov_b32_e32 v98, v0
	v_mov_b32_e32 v99, v0
	v_mov_b32_e32 v100, v0
	v_mov_b32_e32 v101, v0
	v_mov_b32_e32 v102, v0
	v_mov_b32_e32 v103, v0
	v_mov_b32_e32 v116, v0
	v_mov_b32_e32 v117, v0
	v_mov_b32_e32 v118, v0
	v_mov_b32_e32 v119, v0
	v_mov_b32_e32 v120, v0
	v_mov_b32_e32 v121, v0
	v_mov_b32_e32 v122, v0
	v_mov_b32_e32 v123, v0
	v_mov_b32_e32 v72, v0
	v_mov_b32_e32 v73, v0
	v_mov_b32_e32 v74, v0
	v_mov_b32_e32 v75, v0
	v_mov_b32_e32 v76, v0
	v_mov_b32_e32 v77, v0
	v_mov_b32_e32 v78, v0
	v_mov_b32_e32 v79, v0
	v_mov_b32_e32 v88, v0
	v_mov_b32_e32 v89, v0
	v_mov_b32_e32 v90, v0
	v_mov_b32_e32 v91, v0
	v_mov_b32_e32 v92, v0
	v_mov_b32_e32 v93, v0
	v_mov_b32_e32 v94, v0
	v_mov_b32_e32 v95, v0
	v_mov_b32_e32 v104, v0
	v_mov_b32_e32 v105, v0
	v_mov_b32_e32 v106, v0
	v_mov_b32_e32 v107, v0
	v_mov_b32_e32 v108, v0
	v_mov_b32_e32 v109, v0
	v_mov_b32_e32 v110, v0
	v_mov_b32_e32 v111, v0
	v_mov_b32_e32 v128, v0
	v_mov_b32_e32 v129, v0
	v_mov_b32_e32 v130, v0
	v_mov_b32_e32 v131, v0
	v_mov_b32_e32 v132, v0
	v_mov_b32_e32 v133, v0
	v_mov_b32_e32 v134, v0
	v_mov_b32_e32 v135, v0
	s_cmp_lt_u32 s81, 4
	s_cbranch_scc0 .Lsp_skip3
	s_setprio 1

.LBB0_549:
	s_ashr_i32 s31, s30, 31
	s_lshl_b64 s[34:35], s[30:31], 20
	s_add_u32 s34, s40, s34
	s_addc_u32 s35, s41, s35
	s_and_b64 s[36:37], s[2:3], exec
	s_cselect_b32 s1, s35, s7
	s_cselect_b32 s31, s34, s6
	s_ashr_i32 s29, s28, 31
	s_lshl_b64 s[36:37], s[28:29], 20
	s_add_u32 s36, s42, s36
	s_addc_u32 s37, s43, s37
	s_and_b64 s[38:39], s[2:3], exec
	s_cselect_b32 s29, s37, s5
	s_cselect_b32 s61, s36, s4
	s_add_u32 s62, s4, 0x100
	s_addc_u32 s63, s5, 0
	s_add_u32 s4, s6, 0x80080
	v_mov_b32_e32 v0, 0
	s_addc_u32 s5, s7, 0
	s_mov_b32 s64, -2
	v_mov_b32_e32 v1, v0
	v_mov_b32_e32 v2, v0
	v_mov_b32_e32 v3, v0
	v_mov_b32_e32 v4, v0
	v_mov_b32_e32 v5, v0
	v_mov_b32_e32 v6, v0
	v_mov_b32_e32 v7, v0
	v_mov_b32_e32 v16, v0
	v_mov_b32_e32 v17, v0
	v_mov_b32_e32 v18, v0
	v_mov_b32_e32 v19, v0
	v_mov_b32_e32 v20, v0
	v_mov_b32_e32 v21, v0
	v_mov_b32_e32 v22, v0
	v_mov_b32_e32 v23, v0
	v_mov_b32_e32 v32, v0
	v_mov_b32_e32 v33, v0
	v_mov_b32_e32 v34, v0
	v_mov_b32_e32 v35, v0
	v_mov_b32_e32 v36, v0
	v_mov_b32_e32 v37, v0
	v_mov_b32_e32 v38, v0
	v_mov_b32_e32 v39, v0
	v_mov_b32_e32 v48, v0
	v_mov_b32_e32 v49, v0
	v_mov_b32_e32 v50, v0
	v_mov_b32_e32 v51, v0
	v_mov_b32_e32 v52, v0
	v_mov_b32_e32 v53, v0
	v_mov_b32_e32 v54, v0
	v_mov_b32_e32 v55, v0
	v_mov_b32_e32 v8, v0
	v_mov_b32_e32 v9, v0
	v_mov_b32_e32 v10, v0
	v_mov_b32_e32 v11, v0
	v_mov_b32_e32 v12, v0
	v_mov_b32_e32 v13, v0
	v_mov_b32_e32 v14, v0
	v_mov_b32_e32 v15, v0
	v_mov_b32_e32 v24, v0
	v_mov_b32_e32 v25, v0
	v_mov_b32_e32 v26, v0
	v_mov_b32_e32 v27, v0
	v_mov_b32_e32 v28, v0
	v_mov_b32_e32 v29, v0
	v_mov_b32_e32 v30, v0
	v_mov_b32_e32 v31, v0
	v_mov_b32_e32 v40, v0
	v_mov_b32_e32 v41, v0
	v_mov_b32_e32 v42, v0
	v_mov_b32_e32 v43, v0
	v_mov_b32_e32 v44, v0
	v_mov_b32_e32 v45, v0
	v_mov_b32_e32 v46, v0
	v_mov_b32_e32 v47, v0
	v_mov_b32_e32 v56, v0
	v_mov_b32_e32 v57, v0
	v_mov_b32_e32 v58, v0
	v_mov_b32_e32 v59, v0
	v_mov_b32_e32 v60, v0
	v_mov_b32_e32 v61, v0
	v_mov_b32_e32 v62, v0
	v_mov_b32_e32 v63, v0
	v_mov_b32_e32 v64, v0
	v_mov_b32_e32 v65, v0
	v_mov_b32_e32 v66, v0
	v_mov_b32_e32 v67, v0
	v_mov_b32_e32 v68, v0
	v_mov_b32_e32 v69, v0
	v_mov_b32_e32 v70, v0
	v_mov_b32_e32 v71, v0
	v_mov_b32_e32 v80, v0
	v_mov_b32_e32 v81, v0
	v_mov_b32_e32 v82, v0
	v_mov_b32_e32 v83, v0
	v_mov_b32_e32 v84, v0
	v_mov_b32_e32 v85, v0
	v_mov_b32_e32 v86, v0
	v_mov_b32_e32 v87, v0
	v_mov_b32_e32 v96, v0
	v_mov_b32_e32 v97, v0
	v_mov_b32_e32 v98, v0
	v_mov_b32_e32 v99, v0
	v_mov_b32_e32 v100, v0
	v_mov_b32_e32 v101, v0
	v_mov_b32_e32 v102, v0
	v_mov_b32_e32 v103, v0
	v_mov_b32_e32 v112, v0
	v_mov_b32_e32 v113, v0
	v_mov_b32_e32 v114, v0
	v_mov_b32_e32 v115, v0
	v_mov_b32_e32 v116, v0
	v_mov_b32_e32 v117, v0
	v_mov_b32_e32 v118, v0
	v_mov_b32_e32 v119, v0
	v_mov_b32_e32 v72, v0
	v_mov_b32_e32 v73, v0
	v_mov_b32_e32 v74, v0
	v_mov_b32_e32 v75, v0
	v_mov_b32_e32 v76, v0
	v_mov_b32_e32 v77, v0
	v_mov_b32_e32 v78, v0
	v_mov_b32_e32 v79, v0
	v_mov_b32_e32 v88, v0
	v_mov_b32_e32 v89, v0
	v_mov_b32_e32 v90, v0
	v_mov_b32_e32 v91, v0
	v_mov_b32_e32 v92, v0
	v_mov_b32_e32 v93, v0
	v_mov_b32_e32 v94, v0
	v_mov_b32_e32 v95, v0
	v_mov_b32_e32 v104, v0
	v_mov_b32_e32 v105, v0
	v_mov_b32_e32 v106, v0
	v_mov_b32_e32 v107, v0
	v_mov_b32_e32 v108, v0
	v_mov_b32_e32 v109, v0
	v_mov_b32_e32 v110, v0
	v_mov_b32_e32 v111, v0
	v_mov_b32_e32 v120, v0
	v_mov_b32_e32 v121, v0
	v_mov_b32_e32 v122, v0
	v_mov_b32_e32 v123, v0
	v_mov_b32_e32 v124, v0
	v_mov_b32_e32 v125, v0
	v_mov_b32_e32 v126, v0
	v_mov_b32_e32 v127, v0
	s_cmp_lt_u32 s81, 4
	s_cbranch_scc0 .Lsp_skip4
	s_setprio 1

.LBB0_634:
	s_ashr_i32 s21, s20, 31
	s_mul_i32 s22, s20, 0x810000
	s_mov_b32 s23, 0
	s_add_u32 s22, s33, s22
	s_addc_u32 s23, s38, s23
	s_and_b64 s[24:25], s[4:5], exec
	s_cselect_b32 s21, s23, s35
	s_cselect_b32 s27, s22, s34
	s_ashr_i32 s19, s18, 31
	s_lshl_b64 s[24:25], s[18:19], 23
	s_add_u32 s24, s39, s24
	s_addc_u32 s25, s40, s25
	s_and_b64 s[36:37], s[4:5], exec
	s_cselect_b32 s19, s25, s31
	s_cselect_b32 s55, s24, s30
	s_add_u32 s56, s30, 0x100
	s_addc_u32 s57, s31, 0
	s_add_u32 s30, s34, 0x408080
	v_mov_b32_e32 v0, 0
	s_addc_u32 s31, s35, 0
	s_mov_b32 s58, -2
	s_waitcnt lgkmcnt(0)
	v_mov_b32_e32 v1, v0
	v_mov_b32_e32 v2, v0
	v_mov_b32_e32 v3, v0
	v_mov_b32_e32 v4, v0
	v_mov_b32_e32 v5, v0
	v_mov_b32_e32 v6, v0
	v_mov_b32_e32 v7, v0
	v_mov_b32_e32 v16, v0
	v_mov_b32_e32 v17, v0
	v_mov_b32_e32 v18, v0
	v_mov_b32_e32 v19, v0
	v_mov_b32_e32 v20, v0
	v_mov_b32_e32 v21, v0
	v_mov_b32_e32 v22, v0
	v_mov_b32_e32 v23, v0
	v_mov_b32_e32 v32, v0
	v_mov_b32_e32 v33, v0
	v_mov_b32_e32 v34, v0
	v_mov_b32_e32 v35, v0
	v_mov_b32_e32 v36, v0
	v_mov_b32_e32 v37, v0
	v_mov_b32_e32 v38, v0
	v_mov_b32_e32 v39, v0
	v_mov_b32_e32 v48, v0
	v_mov_b32_e32 v49, v0
	v_mov_b32_e32 v50, v0
	v_mov_b32_e32 v51, v0
	v_mov_b32_e32 v52, v0
	v_mov_b32_e32 v53, v0
	v_mov_b32_e32 v54, v0
	v_mov_b32_e32 v55, v0
	v_mov_b32_e32 v8, v0
	v_mov_b32_e32 v9, v0
	v_mov_b32_e32 v10, v0
	v_mov_b32_e32 v11, v0
	v_mov_b32_e32 v12, v0
	v_mov_b32_e32 v13, v0
	v_mov_b32_e32 v14, v0
	v_mov_b32_e32 v15, v0
	v_mov_b32_e32 v24, v0
	v_mov_b32_e32 v25, v0
	v_mov_b32_e32 v26, v0
	v_mov_b32_e32 v27, v0
	v_mov_b32_e32 v28, v0
	v_mov_b32_e32 v29, v0
	v_mov_b32_e32 v30, v0
	v_mov_b32_e32 v31, v0
	v_mov_b32_e32 v40, v0
	v_mov_b32_e32 v41, v0
	v_mov_b32_e32 v42, v0
	v_mov_b32_e32 v43, v0
	v_mov_b32_e32 v44, v0
	v_mov_b32_e32 v45, v0
	v_mov_b32_e32 v46, v0
	v_mov_b32_e32 v47, v0
	v_mov_b32_e32 v56, v0
	v_mov_b32_e32 v57, v0
	v_mov_b32_e32 v58, v0
	v_mov_b32_e32 v59, v0
	v_mov_b32_e32 v60, v0
	v_mov_b32_e32 v61, v0
	v_mov_b32_e32 v62, v0
	v_mov_b32_e32 v63, v0
	v_mov_b32_e32 v64, v0
	v_mov_b32_e32 v65, v0
	v_mov_b32_e32 v66, v0
	v_mov_b32_e32 v67, v0
	v_mov_b32_e32 v68, v0
	v_mov_b32_e32 v69, v0
	v_mov_b32_e32 v70, v0
	v_mov_b32_e32 v71, v0
	v_mov_b32_e32 v80, v0
	v_mov_b32_e32 v81, v0
	v_mov_b32_e32 v82, v0
	v_mov_b32_e32 v83, v0
	v_mov_b32_e32 v84, v0
	v_mov_b32_e32 v85, v0
	v_mov_b32_e32 v86, v0
	v_mov_b32_e32 v87, v0
	v_mov_b32_e32 v96, v0
	v_mov_b32_e32 v97, v0
	v_mov_b32_e32 v98, v0
	v_mov_b32_e32 v99, v0
	v_mov_b32_e32 v100, v0
	v_mov_b32_e32 v101, v0
	v_mov_b32_e32 v102, v0
	v_mov_b32_e32 v103, v0
	v_mov_b32_e32 v116, v0
	v_mov_b32_e32 v117, v0
	v_mov_b32_e32 v118, v0
	v_mov_b32_e32 v119, v0
	v_mov_b32_e32 v120, v0
	v_mov_b32_e32 v121, v0
	v_mov_b32_e32 v122, v0
	v_mov_b32_e32 v123, v0
	v_mov_b32_e32 v72, v0
	v_mov_b32_e32 v73, v0
	v_mov_b32_e32 v74, v0
	v_mov_b32_e32 v75, v0
	v_mov_b32_e32 v76, v0
	v_mov_b32_e32 v77, v0
	v_mov_b32_e32 v78, v0
	v_mov_b32_e32 v79, v0
	v_mov_b32_e32 v88, v0
	v_mov_b32_e32 v89, v0
	v_mov_b32_e32 v90, v0
	v_mov_b32_e32 v91, v0
	v_mov_b32_e32 v92, v0
	v_mov_b32_e32 v93, v0
	v_mov_b32_e32 v94, v0
	v_mov_b32_e32 v95, v0
	v_mov_b32_e32 v104, v0
	v_mov_b32_e32 v105, v0
	v_mov_b32_e32 v106, v0
	v_mov_b32_e32 v107, v0
	v_mov_b32_e32 v108, v0
	v_mov_b32_e32 v109, v0
	v_mov_b32_e32 v110, v0
	v_mov_b32_e32 v111, v0
	v_mov_b32_e32 v128, v0
	v_mov_b32_e32 v129, v0
	v_mov_b32_e32 v130, v0
	v_mov_b32_e32 v131, v0
	v_mov_b32_e32 v132, v0
	v_mov_b32_e32 v133, v0
	v_mov_b32_e32 v134, v0
	v_mov_b32_e32 v135, v0
	s_cmp_lt_u32 s81, 4
	s_cbranch_scc0 .Lsp_skip5
	s_setprio 1

.LBB0_725:
	s_ashr_i32 s23, s22, 31
	s_lshl_b64 s[24:25], s[22:23], 20
	s_add_u32 s24, s30, s24
	s_addc_u32 s25, s31, s25
	s_and_b64 s[26:27], s[2:3], exec
	s_cselect_b32 s1, s25, s7
	s_cselect_b32 s23, s24, s6
	s_ashr_i32 s21, s20, 31
	s_lshl_b64 s[26:27], s[20:21], 20
	s_add_u32 s26, s33, s26
	s_addc_u32 s27, s34, s27
	s_and_b64 s[28:29], s[2:3], exec
	s_cselect_b32 s21, s27, s5
	s_cselect_b32 s51, s26, s4
	s_add_u32 s52, s4, 0x100
	s_addc_u32 s53, s5, 0
	s_add_u32 s4, s6, 0x80080
	v_mov_b32_e32 v0, 0
	s_addc_u32 s5, s7, 0
	s_mov_b32 s54, -2
	v_mov_b32_e32 v1, v0
	v_mov_b32_e32 v2, v0
	v_mov_b32_e32 v3, v0
	v_mov_b32_e32 v4, v0
	v_mov_b32_e32 v5, v0
	v_mov_b32_e32 v6, v0
	v_mov_b32_e32 v7, v0
	v_mov_b32_e32 v16, v0
	v_mov_b32_e32 v17, v0
	v_mov_b32_e32 v18, v0
	v_mov_b32_e32 v19, v0
	v_mov_b32_e32 v20, v0
	v_mov_b32_e32 v21, v0
	v_mov_b32_e32 v22, v0
	v_mov_b32_e32 v23, v0
	v_mov_b32_e32 v32, v0
	v_mov_b32_e32 v33, v0
	v_mov_b32_e32 v34, v0
	v_mov_b32_e32 v35, v0
	v_mov_b32_e32 v36, v0
	v_mov_b32_e32 v37, v0
	v_mov_b32_e32 v38, v0
	v_mov_b32_e32 v39, v0
	v_mov_b32_e32 v48, v0
	v_mov_b32_e32 v49, v0
	v_mov_b32_e32 v50, v0
	v_mov_b32_e32 v51, v0
	v_mov_b32_e32 v52, v0
	v_mov_b32_e32 v53, v0
	v_mov_b32_e32 v54, v0
	v_mov_b32_e32 v55, v0
	v_mov_b32_e32 v8, v0
	v_mov_b32_e32 v9, v0
	v_mov_b32_e32 v10, v0
	v_mov_b32_e32 v11, v0
	v_mov_b32_e32 v12, v0
	v_mov_b32_e32 v13, v0
	v_mov_b32_e32 v14, v0
	v_mov_b32_e32 v15, v0
	v_mov_b32_e32 v24, v0
	v_mov_b32_e32 v25, v0
	v_mov_b32_e32 v26, v0
	v_mov_b32_e32 v27, v0
	v_mov_b32_e32 v28, v0
	v_mov_b32_e32 v29, v0
	v_mov_b32_e32 v30, v0
	v_mov_b32_e32 v31, v0
	v_mov_b32_e32 v40, v0
	v_mov_b32_e32 v41, v0
	v_mov_b32_e32 v42, v0
	v_mov_b32_e32 v43, v0
	v_mov_b32_e32 v44, v0
	v_mov_b32_e32 v45, v0
	v_mov_b32_e32 v46, v0
	v_mov_b32_e32 v47, v0
	v_mov_b32_e32 v56, v0
	v_mov_b32_e32 v57, v0
	v_mov_b32_e32 v58, v0
	v_mov_b32_e32 v59, v0
	v_mov_b32_e32 v60, v0
	v_mov_b32_e32 v61, v0
	v_mov_b32_e32 v62, v0
	v_mov_b32_e32 v63, v0
	v_mov_b32_e32 v64, v0
	v_mov_b32_e32 v65, v0
	v_mov_b32_e32 v66, v0
	v_mov_b32_e32 v67, v0
	v_mov_b32_e32 v68, v0
	v_mov_b32_e32 v69, v0
	v_mov_b32_e32 v70, v0
	v_mov_b32_e32 v71, v0
	v_mov_b32_e32 v80, v0
	v_mov_b32_e32 v81, v0
	v_mov_b32_e32 v82, v0
	v_mov_b32_e32 v83, v0
	v_mov_b32_e32 v84, v0
	v_mov_b32_e32 v85, v0
	v_mov_b32_e32 v86, v0
	v_mov_b32_e32 v87, v0
	v_mov_b32_e32 v96, v0
	v_mov_b32_e32 v97, v0
	v_mov_b32_e32 v98, v0
	v_mov_b32_e32 v99, v0
	v_mov_b32_e32 v100, v0
	v_mov_b32_e32 v101, v0
	v_mov_b32_e32 v102, v0
	v_mov_b32_e32 v103, v0
	v_mov_b32_e32 v112, v0
	v_mov_b32_e32 v113, v0
	v_mov_b32_e32 v114, v0
	v_mov_b32_e32 v115, v0
	v_mov_b32_e32 v116, v0
	v_mov_b32_e32 v117, v0
	v_mov_b32_e32 v118, v0
	v_mov_b32_e32 v119, v0
	v_mov_b32_e32 v72, v0
	v_mov_b32_e32 v73, v0
	v_mov_b32_e32 v74, v0
	v_mov_b32_e32 v75, v0
	v_mov_b32_e32 v76, v0
	v_mov_b32_e32 v77, v0
	v_mov_b32_e32 v78, v0
	v_mov_b32_e32 v79, v0
	v_mov_b32_e32 v88, v0
	v_mov_b32_e32 v89, v0
	v_mov_b32_e32 v90, v0
	v_mov_b32_e32 v91, v0
	v_mov_b32_e32 v92, v0
	v_mov_b32_e32 v93, v0
	v_mov_b32_e32 v94, v0
	v_mov_b32_e32 v95, v0
	v_mov_b32_e32 v104, v0
	v_mov_b32_e32 v105, v0
	v_mov_b32_e32 v106, v0
	v_mov_b32_e32 v107, v0
	v_mov_b32_e32 v108, v0
	v_mov_b32_e32 v109, v0
	v_mov_b32_e32 v110, v0
	v_mov_b32_e32 v111, v0
	v_mov_b32_e32 v120, v0
	v_mov_b32_e32 v121, v0
	v_mov_b32_e32 v122, v0
	v_mov_b32_e32 v123, v0
	v_mov_b32_e32 v124, v0
	v_mov_b32_e32 v125, v0
	v_mov_b32_e32 v126, v0
	v_mov_b32_e32 v127, v0
	s_cmp_lt_u32 s81, 4
	s_cbranch_scc0 .Lsp_skip6
	s_setprio 1

.LBB0_1254:
	s_ashr_i32 s23, s22, 31
	s_lshl_b64 s[24:25], s[22:23], 19
	s_add_u32 s24, s19, s24
	s_addc_u32 s25, s33, s25
	s_and_b64 s[26:27], s[4:5], exec
	s_cselect_b32 s23, s25, s37
	s_cselect_b32 s29, s24, s36
	s_ashr_i32 s21, s20, 31
	s_lshl_b64 s[26:27], s[20:21], 19
	s_add_u32 s26, s40, s26
	s_addc_u32 s27, s41, s27
	s_and_b64 s[38:39], s[4:5], exec
	s_cselect_b32 s21, s27, s35
	s_cselect_b32 s56, s26, s34
	s_add_u32 s57, s34, 0x100
	s_addc_u32 s58, s35, 0
	s_add_u32 s34, s36, 0x40080
	v_mov_b32_e32 v32, 0
	s_addc_u32 s35, s37, 0
	s_mov_b32 s59, -2
	v_mov_b32_e32 v33, v32
	v_mov_b32_e32 v34, v32
	v_mov_b32_e32 v35, v32
	v_mov_b32_e32 v36, v32
	v_mov_b32_e32 v37, v32
	v_mov_b32_e32 v38, v32
	v_mov_b32_e32 v39, v32
	v_mov_b32_e32 v48, v32
	v_mov_b32_e32 v49, v32
	v_mov_b32_e32 v50, v32
	v_mov_b32_e32 v51, v32
	v_mov_b32_e32 v52, v32
	v_mov_b32_e32 v53, v32
	v_mov_b32_e32 v54, v32
	v_mov_b32_e32 v55, v32
	v_mov_b32_e32 v64, v32
	v_mov_b32_e32 v65, v32
	v_mov_b32_e32 v66, v32
	v_mov_b32_e32 v67, v32
	v_mov_b32_e32 v68, v32
	v_mov_b32_e32 v69, v32
	v_mov_b32_e32 v70, v32
	v_mov_b32_e32 v71, v32
	v_mov_b32_e32 v80, v32
	v_mov_b32_e32 v81, v32
	v_mov_b32_e32 v82, v32
	v_mov_b32_e32 v83, v32
	v_mov_b32_e32 v84, v32
	v_mov_b32_e32 v85, v32
	v_mov_b32_e32 v86, v32
	v_mov_b32_e32 v87, v32
	v_mov_b32_e32 v40, v32
	v_mov_b32_e32 v41, v32
	v_mov_b32_e32 v42, v32
	v_mov_b32_e32 v43, v32
	v_mov_b32_e32 v44, v32
	v_mov_b32_e32 v45, v32
	v_mov_b32_e32 v46, v32
	v_mov_b32_e32 v47, v32
	v_mov_b32_e32 v56, v32
	v_mov_b32_e32 v57, v32
	v_mov_b32_e32 v58, v32
	v_mov_b32_e32 v59, v32
	v_mov_b32_e32 v60, v32
	v_mov_b32_e32 v61, v32
	v_mov_b32_e32 v62, v32
	v_mov_b32_e32 v63, v32
	v_mov_b32_e32 v72, v32
	v_mov_b32_e32 v73, v32
	v_mov_b32_e32 v74, v32
	v_mov_b32_e32 v75, v32
	v_mov_b32_e32 v76, v32
	v_mov_b32_e32 v77, v32
	v_mov_b32_e32 v78, v32
	v_mov_b32_e32 v79, v32
	v_mov_b32_e32 v88, v32
	v_mov_b32_e32 v89, v32
	v_mov_b32_e32 v90, v32
	v_mov_b32_e32 v91, v32
	v_mov_b32_e32 v92, v32
	v_mov_b32_e32 v93, v32
	v_mov_b32_e32 v94, v32
	v_mov_b32_e32 v95, v32
	v_mov_b32_e32 v96, v32
	v_mov_b32_e32 v97, v32
	v_mov_b32_e32 v98, v32
	v_mov_b32_e32 v99, v32
	v_mov_b32_e32 v100, v32
	v_mov_b32_e32 v101, v32
	v_mov_b32_e32 v102, v32
	v_mov_b32_e32 v103, v32
	v_mov_b32_e32 v112, v32
	v_mov_b32_e32 v113, v32
	v_mov_b32_e32 v114, v32
	v_mov_b32_e32 v115, v32
	v_mov_b32_e32 v116, v32
	v_mov_b32_e32 v117, v32
	v_mov_b32_e32 v118, v32
	v_mov_b32_e32 v119, v32
	v_mov_b32_e32 v128, v32
	v_mov_b32_e32 v129, v32
	v_mov_b32_e32 v130, v32
	v_mov_b32_e32 v131, v32
	v_mov_b32_e32 v132, v32
	v_mov_b32_e32 v133, v32
	v_mov_b32_e32 v134, v32
	v_mov_b32_e32 v135, v32
	v_mov_b32_e32 v144, v32
	v_mov_b32_e32 v145, v32
	v_mov_b32_e32 v146, v32
	v_mov_b32_e32 v147, v32
	v_mov_b32_e32 v148, v32
	v_mov_b32_e32 v149, v32
	v_mov_b32_e32 v150, v32
	v_mov_b32_e32 v151, v32
	v_mov_b32_e32 v104, v32
	v_mov_b32_e32 v105, v32
	v_mov_b32_e32 v106, v32
	v_mov_b32_e32 v107, v32
	v_mov_b32_e32 v108, v32
	v_mov_b32_e32 v109, v32
	v_mov_b32_e32 v110, v32
	v_mov_b32_e32 v111, v32
	v_mov_b32_e32 v120, v32
	v_mov_b32_e32 v121, v32
	v_mov_b32_e32 v122, v32
	v_mov_b32_e32 v123, v32
	v_mov_b32_e32 v124, v32
	v_mov_b32_e32 v125, v32
	v_mov_b32_e32 v126, v32
	v_mov_b32_e32 v127, v32
	v_mov_b32_e32 v136, v32
	v_mov_b32_e32 v137, v32
	v_mov_b32_e32 v138, v32
	v_mov_b32_e32 v139, v32
	v_mov_b32_e32 v140, v32
	v_mov_b32_e32 v141, v32
	v_mov_b32_e32 v142, v32
	v_mov_b32_e32 v143, v32
	v_mov_b32_e32 v152, v32
	v_mov_b32_e32 v153, v32
	v_mov_b32_e32 v154, v32
	v_mov_b32_e32 v155, v32
	v_mov_b32_e32 v156, v32
	v_mov_b32_e32 v157, v32
	v_mov_b32_e32 v158, v32
	v_mov_b32_e32 v159, v32
	s_cmp_lt_u32 s81, 4
	s_cbranch_scc0 .Lsp_skip7
	s_setprio 1

.LBB0_1355:
	s_ashr_i32 s23, s22, 31
	s_lshl_b64 s[24:25], s[22:23], 20
	s_add_u32 s24, s38, s24
	s_addc_u32 s25, s39, s25
	s_and_b64 s[26:27], s[2:3], exec
	s_cselect_b32 s1, s25, s35
	s_cselect_b32 s23, s24, s34
	s_ashr_i32 s21, s20, 31
	s_lshl_b64 s[26:27], s[20:21], 20
	s_add_u32 s26, s40, s26
	s_addc_u32 s27, s41, s27
	s_and_b64 s[36:37], s[2:3], exec
	s_cselect_b32 s21, s27, s31
	s_cselect_b32 s29, s26, s30
	s_add_u32 s33, s30, 0x100
	s_addc_u32 s57, s31, 0
	s_add_u32 s30, s34, 0x80080
	v_mov_b32_e32 v0, 0
	s_addc_u32 s31, s35, 0
	s_mov_b32 s58, -2
	v_mov_b32_e32 v1, v0
	v_mov_b32_e32 v2, v0
	v_mov_b32_e32 v3, v0
	v_mov_b32_e32 v4, v0
	v_mov_b32_e32 v5, v0
	v_mov_b32_e32 v6, v0
	v_mov_b32_e32 v7, v0
	v_mov_b32_e32 v16, v0
	v_mov_b32_e32 v17, v0
	v_mov_b32_e32 v18, v0
	v_mov_b32_e32 v19, v0
	v_mov_b32_e32 v20, v0
	v_mov_b32_e32 v21, v0
	v_mov_b32_e32 v22, v0
	v_mov_b32_e32 v23, v0
	v_mov_b32_e32 v32, v0
	v_mov_b32_e32 v33, v0
	v_mov_b32_e32 v34, v0
	v_mov_b32_e32 v35, v0
	v_mov_b32_e32 v36, v0
	v_mov_b32_e32 v37, v0
	v_mov_b32_e32 v38, v0
	v_mov_b32_e32 v39, v0
	v_mov_b32_e32 v48, v0
	v_mov_b32_e32 v49, v0
	v_mov_b32_e32 v50, v0
	v_mov_b32_e32 v51, v0
	v_mov_b32_e32 v52, v0
	v_mov_b32_e32 v53, v0
	v_mov_b32_e32 v54, v0
	v_mov_b32_e32 v55, v0
	v_mov_b32_e32 v8, v0
	v_mov_b32_e32 v9, v0
	v_mov_b32_e32 v10, v0
	v_mov_b32_e32 v11, v0
	v_mov_b32_e32 v12, v0
	v_mov_b32_e32 v13, v0
	v_mov_b32_e32 v14, v0
	v_mov_b32_e32 v15, v0
	v_mov_b32_e32 v24, v0
	v_mov_b32_e32 v25, v0
	v_mov_b32_e32 v26, v0
	v_mov_b32_e32 v27, v0
	v_mov_b32_e32 v28, v0
	v_mov_b32_e32 v29, v0
	v_mov_b32_e32 v30, v0
	v_mov_b32_e32 v31, v0
	v_mov_b32_e32 v40, v0
	v_mov_b32_e32 v41, v0
	v_mov_b32_e32 v42, v0
	v_mov_b32_e32 v43, v0
	v_mov_b32_e32 v44, v0
	v_mov_b32_e32 v45, v0
	v_mov_b32_e32 v46, v0
	v_mov_b32_e32 v47, v0
	v_mov_b32_e32 v56, v0
	v_mov_b32_e32 v57, v0
	v_mov_b32_e32 v58, v0
	v_mov_b32_e32 v59, v0
	v_mov_b32_e32 v60, v0
	v_mov_b32_e32 v61, v0
	v_mov_b32_e32 v62, v0
	v_mov_b32_e32 v63, v0
	v_mov_b32_e32 v64, v0
	v_mov_b32_e32 v65, v0
	v_mov_b32_e32 v66, v0
	v_mov_b32_e32 v67, v0
	v_mov_b32_e32 v68, v0
	v_mov_b32_e32 v69, v0
	v_mov_b32_e32 v70, v0
	v_mov_b32_e32 v71, v0
	v_mov_b32_e32 v80, v0
	v_mov_b32_e32 v81, v0
	v_mov_b32_e32 v82, v0
	v_mov_b32_e32 v83, v0
	v_mov_b32_e32 v84, v0
	v_mov_b32_e32 v85, v0
	v_mov_b32_e32 v86, v0
	v_mov_b32_e32 v87, v0
	v_mov_b32_e32 v96, v0
	v_mov_b32_e32 v97, v0
	v_mov_b32_e32 v98, v0
	v_mov_b32_e32 v99, v0
	v_mov_b32_e32 v100, v0
	v_mov_b32_e32 v101, v0
	v_mov_b32_e32 v102, v0
	v_mov_b32_e32 v103, v0
	v_mov_b32_e32 v112, v0
	v_mov_b32_e32 v113, v0
	v_mov_b32_e32 v114, v0
	v_mov_b32_e32 v115, v0
	v_mov_b32_e32 v116, v0
	v_mov_b32_e32 v117, v0
	v_mov_b32_e32 v118, v0
	v_mov_b32_e32 v119, v0
	v_mov_b32_e32 v72, v0
	v_mov_b32_e32 v73, v0
	v_mov_b32_e32 v74, v0
	v_mov_b32_e32 v75, v0
	v_mov_b32_e32 v76, v0
	v_mov_b32_e32 v77, v0
	v_mov_b32_e32 v78, v0
	v_mov_b32_e32 v79, v0
	v_mov_b32_e32 v88, v0
	v_mov_b32_e32 v89, v0
	v_mov_b32_e32 v90, v0
	v_mov_b32_e32 v91, v0
	v_mov_b32_e32 v92, v0
	v_mov_b32_e32 v93, v0
	v_mov_b32_e32 v94, v0
	v_mov_b32_e32 v95, v0
	v_mov_b32_e32 v104, v0
	v_mov_b32_e32 v105, v0
	v_mov_b32_e32 v106, v0
	v_mov_b32_e32 v107, v0
	v_mov_b32_e32 v108, v0
	v_mov_b32_e32 v109, v0
	v_mov_b32_e32 v110, v0
	v_mov_b32_e32 v111, v0
	v_mov_b32_e32 v120, v0
	v_mov_b32_e32 v121, v0
	v_mov_b32_e32 v122, v0
	v_mov_b32_e32 v123, v0
	v_mov_b32_e32 v124, v0
	v_mov_b32_e32 v125, v0
	v_mov_b32_e32 v126, v0
	v_mov_b32_e32 v127, v0
	s_cmp_lt_u32 s81, 4
	s_cbranch_scc0 .Lsp_skip8
	s_setprio 1

.LBB0_1840:
	s_ashr_i32 s19, s18, 31
	s_lshl_b64 s[20:21], s[18:19], 22
	s_add_u32 s20, s15, s20
	s_addc_u32 s21, s33, s21
	s_and_b64 s[22:23], s[4:5], exec
	s_cselect_b32 s19, s21, s31
	s_cselect_b32 s25, s20, s30
	s_ashr_i32 s17, s16, 31
	s_lshl_b64 s[22:23], s[16:17], 22
	s_add_u32 s22, s36, s22
	s_addc_u32 s23, s37, s23
	s_and_b64 s[34:35], s[4:5], exec
	s_cselect_b32 s17, s23, s29
	s_cselect_b32 s50, s22, s28
	s_add_u32 s51, s28, 0x100
	s_addc_u32 s52, s29, 0
	s_add_u32 s28, s30, 0x200080
	s_waitcnt vmcnt(0) lgkmcnt(0)
	v_mov_b64_e32 v[18:19], v[2:3]
	v_mov_b64_e32 v[22:23], v[6:7]
	v_mov_b64_e32 v[34:35], v[2:3]
	v_mov_b64_e32 v[38:39], v[6:7]
	v_mov_b64_e32 v[50:51], v[2:3]
	v_mov_b64_e32 v[54:55], v[6:7]
	v_mov_b64_e32 v[26:27], v[10:11]
	v_mov_b64_e32 v[30:31], v[14:15]
	v_mov_b64_e32 v[42:43], v[10:11]
	v_mov_b64_e32 v[46:47], v[14:15]
	v_mov_b64_e32 v[58:59], v[10:11]
	v_mov_b64_e32 v[62:63], v[14:15]
	v_mov_b64_e32 v[66:67], v[2:3]
	v_mov_b64_e32 v[70:71], v[6:7]
	v_mov_b64_e32 v[82:83], v[2:3]
	v_mov_b64_e32 v[86:87], v[6:7]
	v_mov_b64_e32 v[98:99], v[2:3]
	v_mov_b64_e32 v[102:103], v[6:7]
	v_mov_b64_e32 v[122:123], v[2:3]
	v_mov_b64_e32 v[130:131], v[6:7]
	v_mov_b64_e32 v[74:75], v[10:11]
	v_mov_b64_e32 v[78:79], v[14:15]
	v_mov_b64_e32 v[90:91], v[10:11]
	v_mov_b64_e32 v[94:95], v[14:15]
	v_mov_b64_e32 v[110:111], v[10:11]
	v_mov_b64_e32 v[114:115], v[14:15]
	v_mov_b64_e32 v[106:107], v[10:11]
	v_mov_b64_e32 v[118:119], v[14:15]
	s_addc_u32 s29, s31, 0
	s_mov_b32 s53, -2
	v_mov_b64_e32 v[16:17], v[0:1]
	v_mov_b64_e32 v[20:21], v[4:5]
	v_mov_b64_e32 v[32:33], v[0:1]
	v_mov_b64_e32 v[36:37], v[4:5]
	v_mov_b64_e32 v[48:49], v[0:1]
	v_mov_b64_e32 v[52:53], v[4:5]
	v_mov_b64_e32 v[24:25], v[8:9]
	v_mov_b64_e32 v[28:29], v[12:13]
	v_mov_b64_e32 v[40:41], v[8:9]
	v_mov_b64_e32 v[44:45], v[12:13]
	v_mov_b64_e32 v[56:57], v[8:9]
	v_mov_b64_e32 v[60:61], v[12:13]
	v_mov_b64_e32 v[64:65], v[0:1]
	v_mov_b64_e32 v[68:69], v[4:5]
	v_mov_b64_e32 v[80:81], v[0:1]
	v_mov_b64_e32 v[84:85], v[4:5]
	v_mov_b64_e32 v[96:97], v[0:1]
	v_mov_b64_e32 v[100:101], v[4:5]
	v_mov_b64_e32 v[120:121], v[0:1]
	v_mov_b64_e32 v[128:129], v[4:5]
	v_mov_b64_e32 v[72:73], v[8:9]
	v_mov_b64_e32 v[76:77], v[12:13]
	v_mov_b64_e32 v[88:89], v[8:9]
	v_mov_b64_e32 v[92:93], v[12:13]
	v_mov_b64_e32 v[108:109], v[8:9]
	v_mov_b64_e32 v[112:113], v[12:13]
	v_mov_b64_e32 v[104:105], v[8:9]
	v_mov_b64_e32 v[116:117], v[12:13]
	s_cmp_lt_u32 s81, 4
	s_cbranch_scc0 .Lsp_skip9
	s_setprio 1
